# first grid barrier: the 16 census loads issued together (one wait) instead of load/wait x16; plus epilogue scale-load hoists and kmean de-serialisation
# speedup vs baseline: 1.0099x; 1.0099x over previous
; __device__ __forceinline__ unsigned xb_ld(unsigned* p)              { return __hip_atomic_load(p, __ATOMIC_RELAXED, __HIP_MEMORY_SCOPE_AGENT); }
; __device__ __forceinline__ void xcd_barrier_complete(unsigned* bar, unsigned x, unsigned& nloc, unsigned& nx) {
;     ...
;     for (;;) {
;         sum = 0u; cnt = 0u; mine = 0u;
; #pragma unroll
;         for (unsigned j = 0; j < 16; ++j) { const unsigned c = xb_ld(&bar[XB_XCNT(j)]); sum += c; cnt += (c > 0u) ? 1u : 0u; mine = (j == x) ? c : mine; }
;         if (sum == G) break;
;         __builtin_amdgcn_s_sleep(1);
;         if ((++sp & 255u) == 0u) { if (xb_ld(&bar[XB_TMO])) break; if (sp > XB_SPIN_CAP) { atomicAdd(&bar[XB_TMO], 1u); break; } }
;     }
;     nloc = mine > 0u ? mine : 1u; nx = cnt > 0u ? cnt : 1u;
.LBB0_808:
	v_readlane_b32 s4, v252, 2
	v_readlane_b32 s5, v252, 3
	s_mov_b64 s[6:7], -1
	s_nop 3
	global_load_dword v1, v145, s[4:5] sc1
	v_readlane_b32 s4, v252, 4
	v_readlane_b32 s5, v252, 5
	s_nop 4
	global_load_dword v2, v145, s[4:5] sc1
	v_readlane_b32 s4, v252, 6
	v_readlane_b32 s5, v252, 7
	s_nop 4
	global_load_dword v3, v145, s[4:5] sc1
	v_readlane_b32 s4, v252, 8
	v_readlane_b32 s5, v252, 9
	s_nop 4
	global_load_dword v4, v145, s[4:5] sc1
	v_readlane_b32 s4, v252, 10
	v_readlane_b32 s5, v252, 11
	s_nop 4
	global_load_dword v5, v145, s[4:5] sc1
	v_readlane_b32 s4, v252, 12
	v_readlane_b32 s5, v252, 13
	s_nop 4
	global_load_dword v6, v145, s[4:5] sc1
	v_readlane_b32 s4, v252, 14
	v_readlane_b32 s5, v252, 15
	s_nop 4
	global_load_dword v7, v145, s[4:5] sc1
	v_readlane_b32 s4, v252, 16
	v_readlane_b32 s5, v252, 17
	s_nop 4
	global_load_dword v8, v145, s[4:5] sc1
	v_readlane_b32 s4, v252, 18
	v_readlane_b32 s5, v252, 19
	s_nop 4
	global_load_dword v9, v145, s[4:5] sc1
	v_readlane_b32 s4, v252, 20
	v_readlane_b32 s5, v252, 21
	s_nop 4
	global_load_dword v10, v145, s[4:5] sc1
	v_readlane_b32 s4, v252, 22
	v_readlane_b32 s5, v252, 23
	s_nop 4
	global_load_dword v11, v145, s[4:5] sc1
	v_readlane_b32 s4, v252, 24
	v_readlane_b32 s5, v252, 25
	s_nop 4
	global_load_dword v12, v145, s[4:5] sc1
	v_readlane_b32 s4, v252, 26
	v_readlane_b32 s5, v252, 27
	s_nop 4
	global_load_dword v13, v145, s[4:5] sc1
	v_readlane_b32 s4, v252, 28
	v_readlane_b32 s5, v252, 29
	s_nop 4
	global_load_dword v14, v145, s[4:5] sc1
	v_readlane_b32 s4, v252, 30
	v_readlane_b32 s5, v252, 31
	s_nop 4
	global_load_dword v15, v145, s[4:5] sc1
	v_readlane_b32 s4, v252, 32
	v_readlane_b32 s5, v252, 33
	s_nop 4
	global_load_dword v16, v145, s[4:5] sc1
	s_mov_b64 s[4:5], -1
	s_waitcnt vmcnt(0)
	v_add_u32_e32 v17, v2, v1
	v_add_u32_e32 v17, v17, v3
	v_add_u32_e32 v17, v17, v4
	v_add_u32_e32 v17, v17, v5
	v_add_u32_e32 v17, v17, v6
	v_add_u32_e32 v17, v17, v7
	v_add_u32_e32 v17, v17, v8
	v_add_u32_e32 v17, v17, v9
	v_add_u32_e32 v17, v17, v10
	v_add_u32_e32 v17, v17, v11
	v_add_u32_e32 v17, v17, v12
	v_add_u32_e32 v17, v17, v13
	v_add_u32_e32 v17, v17, v14
	v_add_u32_e32 v17, v17, v15
	v_add_u32_e32 v17, v17, v16
	v_cmp_eq_u32_e32 vcc, s10, v17
	s_cbranch_vccnz .LBB0_807
	s_and_b32 s4, s11, 0xff
	s_cmp_eq_u32 s4, 0
	s_mov_b64 s[4:5], -1
	s_mov_b64 s[8:9], -1
	s_sleep 1
	s_cbranch_scc0 .LBB0_812
	v_readlane_b32 s4, v252, 0
	v_readlane_b32 s5, v252, 1
	s_nop 4
	global_load_dword v17, v145, s[4:5] sc1
	s_waitcnt vmcnt(0)
	v_cmp_eq_u32_e32 vcc, 0, v17
	s_cbranch_vccnz .LBB0_814
	s_mov_b64 s[8:9], 0
	s_mov_b64 s[4:5], -1
